# lru_carry: per-step addresses as 64-bit stride adds from the first one of each trip (3 instructions per prefetched step instead of 12)
# baseline (speedup 1.0000x reference)
; __device__ __forceinline__ int otid() { int t = __builtin_amdgcn_workitem_id_x(); asm volatile("" : "+v"(t)); return t; }
; __device__ __forceinline__ int obid() { int b = __builtin_amdgcn_workgroup_id_x(); asm volatile("" : "+s"(b)); return b; }
; __device__ __forceinline__ void lru_carry(const float* __restrict__ LSUM, float* __restrict__ LCAR) {
;     for (int id = obid() * 512 + otid(); id < 2048; id += gridDim.x * 512) {
;         const int b = id >> 10, g = (id >> 9) & 1, ch = id & 511; float c = 0.f;
;         for (int st = 0; st < 256; ++st) { const int seg = g ? 255 - st : st; const size_t ix = ((size_t)(b * 256 + seg) * 2 + g) * 512 + ch;
;             LCAR[ix] = c; c = LSUM[2 * ix] * c + LSUM[2 * ix + 1]; }
;     }
; }
.LBB0_503:
	v_readlane_b32 s2, v251, 10
	v_readlane_b32 s3, v251, 11
	s_add_i32 s7, s5, 7
	v_mov_b32_e32 v74, 0xfffff000
	v_mov_b32_e32 v5, 0x1000
	v_cndmask_b32_e32 v74, v74, v5, vcc
	v_ashrrev_i32_e32 v75, 31, v74
	v_lshlrev_b32_e32 v76, 1, v74
	v_mov_b32_e32 v77, v75
	v_mov_b32_e32 v4, s7
	v_mov_b32_e32 v5, s4
	v_cndmask_b32_e32 v4, v4, v5, vcc
	v_or_b32_e32 v4, v4, v3
	v_ashrrev_i32_e32 v5, 31, v4
	v_lshlrev_b64 v[4:5], 10, v[4:5]
	v_or_b32_e32 v4, v4, v2
	v_lshl_add_u64 v[42:43], v[4:5], 2, s[2:3]
	v_lshl_add_u64 v[4:5], v[4:5], 3, s[30:31]
	global_load_dwordx2 v[10:11], v[4:5], off
	v_lshl_add_u64 v[4:5], v[4:5], 0, v[76:77]
	v_lshl_add_u64 v[44:45], v[42:43], 0, v[74:75]
	global_load_dwordx2 v[12:13], v[4:5], off
	v_lshl_add_u64 v[4:5], v[4:5], 0, v[76:77]
	v_lshl_add_u64 v[46:47], v[44:45], 0, v[74:75]
	global_load_dwordx2 v[14:15], v[4:5], off
	v_lshl_add_u64 v[4:5], v[4:5], 0, v[76:77]
	v_lshl_add_u64 v[48:49], v[46:47], 0, v[74:75]
	global_load_dwordx2 v[16:17], v[4:5], off
	v_lshl_add_u64 v[4:5], v[4:5], 0, v[76:77]
	v_lshl_add_u64 v[50:51], v[48:49], 0, v[74:75]
	global_load_dwordx2 v[18:19], v[4:5], off
	v_lshl_add_u64 v[4:5], v[4:5], 0, v[76:77]
	v_lshl_add_u64 v[52:53], v[50:51], 0, v[74:75]
	global_load_dwordx2 v[20:21], v[4:5], off
	v_lshl_add_u64 v[4:5], v[4:5], 0, v[76:77]
	v_lshl_add_u64 v[54:55], v[52:53], 0, v[74:75]
	global_load_dwordx2 v[22:23], v[4:5], off
	v_lshl_add_u64 v[4:5], v[4:5], 0, v[76:77]
	v_lshl_add_u64 v[56:57], v[54:55], 0, v[74:75]
	global_load_dwordx2 v[24:25], v[4:5], off
	v_lshl_add_u64 v[4:5], v[4:5], 0, v[76:77]
	v_lshl_add_u64 v[58:59], v[56:57], 0, v[74:75]
	global_load_dwordx2 v[26:27], v[4:5], off
	v_lshl_add_u64 v[4:5], v[4:5], 0, v[76:77]
	v_lshl_add_u64 v[60:61], v[58:59], 0, v[74:75]
	global_load_dwordx2 v[28:29], v[4:5], off
	v_lshl_add_u64 v[4:5], v[4:5], 0, v[76:77]
	v_lshl_add_u64 v[62:63], v[60:61], 0, v[74:75]
	global_load_dwordx2 v[30:31], v[4:5], off
	v_lshl_add_u64 v[4:5], v[4:5], 0, v[76:77]
	v_lshl_add_u64 v[64:65], v[62:63], 0, v[74:75]
	global_load_dwordx2 v[32:33], v[4:5], off
	v_lshl_add_u64 v[4:5], v[4:5], 0, v[76:77]
	v_lshl_add_u64 v[66:67], v[64:65], 0, v[74:75]
	global_load_dwordx2 v[34:35], v[4:5], off
	v_lshl_add_u64 v[4:5], v[4:5], 0, v[76:77]
	v_lshl_add_u64 v[68:69], v[66:67], 0, v[74:75]
	global_load_dwordx2 v[36:37], v[4:5], off
	v_lshl_add_u64 v[4:5], v[4:5], 0, v[76:77]
	v_lshl_add_u64 v[70:71], v[68:69], 0, v[74:75]
	global_load_dwordx2 v[38:39], v[4:5], off
	v_lshl_add_u64 v[4:5], v[4:5], 0, v[76:77]
	v_lshl_add_u64 v[72:73], v[70:71], 0, v[74:75]
	global_load_dwordx2 v[40:41], v[4:5], off
	global_store_dword v[42:43], v7, off
	s_waitcnt vmcnt(16)
	v_fmac_f32_e32 v11, v7, v10
	global_store_dword v[44:45], v11, off
	s_waitcnt vmcnt(16)
	v_fmac_f32_e32 v13, v11, v12
	global_store_dword v[46:47], v13, off
	s_waitcnt vmcnt(16)
	v_fmac_f32_e32 v15, v13, v14
	global_store_dword v[48:49], v15, off
	s_waitcnt vmcnt(16)
	v_fmac_f32_e32 v17, v15, v16
	global_store_dword v[50:51], v17, off
	s_waitcnt vmcnt(16)
	v_fmac_f32_e32 v19, v17, v18
	global_store_dword v[52:53], v19, off
	s_waitcnt vmcnt(16)
	v_fmac_f32_e32 v21, v19, v20
	global_store_dword v[54:55], v21, off
	s_waitcnt vmcnt(16)
	v_fmac_f32_e32 v23, v21, v22
	global_store_dword v[56:57], v23, off
	s_waitcnt vmcnt(16)
	v_fmac_f32_e32 v25, v23, v24
	global_store_dword v[58:59], v25, off
	s_waitcnt vmcnt(16)
	v_fmac_f32_e32 v27, v25, v26
	global_store_dword v[60:61], v27, off
	s_waitcnt vmcnt(16)
	v_fmac_f32_e32 v29, v27, v28
	global_store_dword v[62:63], v29, off
	s_waitcnt vmcnt(16)
	v_fmac_f32_e32 v31, v29, v30
	global_store_dword v[64:65], v31, off
	s_waitcnt vmcnt(16)
	v_fmac_f32_e32 v33, v31, v32
	global_store_dword v[66:67], v33, off
	s_waitcnt vmcnt(16)
	v_fmac_f32_e32 v35, v33, v34
	global_store_dword v[68:69], v35, off
	s_waitcnt vmcnt(16)
	v_fmac_f32_e32 v37, v35, v36
	global_store_dword v[70:71], v37, off
	s_waitcnt vmcnt(16)
	v_fmac_f32_e32 v39, v37, v38
	global_store_dword v[72:73], v39, off
	s_waitcnt vmcnt(16)
	v_fmac_f32_e32 v41, v39, v40
	v_mov_b32_e32 v7, v41
	s_add_i32 s4, s4, 16
	s_add_i32 s5, s5, -16
	s_cmpk_eq_i32 s4, 0x100
	s_cbranch_scc0 .LBB0_503
	s_waitcnt vmcnt(0)
	v_readlane_b32 s2, v251, 43
	s_nop 1
	v_add_u32_e32 v1, s2, v1
	v_cmp_lt_i32_e32 vcc, s14, v1
	s_or_b64 s[24:25], vcc, s[24:25]
	s_andn2_b64 exec, exec, s[24:25]
	s_cbranch_execnz .LBB0_502
